# GEMM K-loop: LDS-DMA landing waits distributed: vmcnt(10) before six LDS-section barriers instead of vmcnt(6) before two (five-stage latency budget per DMA)
# baseline (speedup 1.0000x reference)
; #define LDA(dst, b, h) for (int m = 0; m < 4; ++m) for (int k = 0; k < 2; ++k) \
;     dst[m][k] = *reinterpret_cast<const bf16x8*>(SA(b, h) + lds_byte(wr * 64 + m * 16 + fr, k * 32 + fq * 8))
; #define LDB(dst, b, h) for (int n = 0; n < 2; ++n) for (int k = 0; k < 2; ++k) \
;     dst[n][k] = *reinterpret_cast<const bf16x8*>(SB(b, h) + lds_byte(wc * 32 + n * 16 + fr, k * 32 + fq * 8))
; #define MMA(ai, bj, At_, Bt_) do { __builtin_amdgcn_s_setprio(1); \
;     for (int m = 0; m < 4; ++m) for (int n = 0; n < 2; ++n) for (int k = 0; k < 2; ++k) \
;       acc[ai][bj][m][n] = __builtin_amdgcn_mfma_f32_16x16x32_bf16(Bt_[n][k], At_[m][k], acc[ai][bj][m][n], 0, 0, 0); \
;     __builtin_amdgcn_s_setprio(0); } while (0)
; #define WAIT_L(n) asm volatile("s_waitcnt lgkmcnt(" #n ")" ::: "memory")
; #define BAR __builtin_amdgcn_s_barrier()
; #define SCHED __builtin_amdgcn_sched_barrier(0)
; #define STG(P, PTR, LD, O0) do { const bf16_t* _g = (PTR); \
;     __builtin_amdgcn_global_load_lds((const unsigned*)(_g + O0), (lds_u32*)((P) + swave * 1024), 16, 0, 0); \
;     __builtin_amdgcn_global_load_lds((const unsigned*)(_g + (size_t)64 * (LD) + O0), (lds_u32*)((P) + swave * 1024 + 8192), 16, 0, 0); } while (0)
; #define LDA(dst, b, h) for (int m = 0; m < 4; ++m) for (int k = 0; k < 2; ++k) \
;     dst[m][k] = *reinterpret_cast<const bf16x8*>(SA(b, h) + lds_byte(wr * 64 + m * 16 + fr, k * 32 + fq * 8))
; #define LDB(dst, b, h) for (int n = 0; n < 2; ++n) for (int k = 0; k < 2; ++k) \
;     dst[n][k] = *reinterpret_cast<const bf16x8*>(SB(b, h) + lds_byte(wc * 32 + n * 16 + fr, k * 32 + fq * 8))
; __device__ __forceinline__ void gemm_stream(int swave, const GemmJob& J, char* shm, int vb, int G) {
;     ...
;       const bool last = (t == nt - 2);
;       const bf16_t* xA = last ? nA : cA; const bf16_t* xA1 = last ? nA1 : cA1; const int k2 = last ? 0 : t + 2;
;       const bf16_t* b2 = last ? nB : cB + (size_t)(t + 2) * 64; const bf16_t* b3 = b2 + 64;
;       LDB(B0, 0, 0); SCHED; LDA(At, 0, 0); STGA(SA(1, 1), cA, cA1, t + 1, 1);
;       WAIT_L(8); BAR; WAIT_L(0); MMA(0, 0, At, B0); BAR; SCHED;
;       LDB(B1, 0, 1); STG(SB(0, 0), b2, ldb, offB0);
;       BAR; WAIT_L(0); MMA(0, 1, At, B1); BAR;
;       LDA(At, 0, 1); STGA(SA(0, 0), xA, xA1, k2, 0);
;       BAR; WAIT_L(0); MMA(1, 0, At, B0); BAR; SCHED;
;       STG(SB(0, 1), b2 + hB, ldb, offB0);
.LBB0_729:
	ds_read_b128 v[164:167], v139
	ds_read_b128 v[168:171], v139 offset:1024
	ds_read_b128 v[172:175], v139 offset:2048
	ds_read_b128 v[176:179], v139 offset:3072
	s_cmp_eq_u32 s49, s29
	s_cselect_b64 s[68:69], -1, 0
	s_and_b64 s[64:65], s[68:69], exec
	s_cselect_b32 s52, s10, s8
	s_cselect_b32 s64, s11, s9
	s_add_i32 s33, s2, 2
	s_and_b64 s[68:69], s[68:69], exec
	s_cselect_b32 s71, s15, s21
	s_cselect_b32 s70, s14, s20
	s_cselect_b32 s68, 0, s33
	s_cselect_b32 s65, s12, s16
	s_cselect_b32 s66, s13, s17
	s_or_b32 s2, s2, 1
	s_cmp_lt_u32 s2, s36
	s_cselect_b64 vcc, -1, 0
	s_and_b64 s[2:3], vcc, exec
	s_cselect_b32 s3, 0, s36
	s_cselect_b32 s2, s38, s37
	s_not_b32 s3, s3
	s_add_i32 s94, s3, s29
	s_and_b64 s[72:73], vcc, exec
	s_cselect_b32 s3, s9, s17
	s_cselect_b32 s69, s8, s16
	s_lshl_b64 s[72:73], s[94:95], 7
	s_add_u32 s69, s69, s72
	s_addc_u32 s74, s3, s73
	s_mov_b32 s3, s95
	s_lshl_b64 s[72:73], s[2:3], 8
	s_add_u32 s72, s69, s72
	v_cndmask_b32_e32 v2, v138, v0, vcc
	s_addc_u32 s73, s74, s73
	s_add_i32 m0, s42, 0xc000
	s_lshl_b64 s[2:3], s[2:3], 7
	v_lshlrev_b64 v[212:213], 1, v[2:3]
	s_add_u32 s2, s72, s2
	v_lshl_add_u64 v[214:215], s[72:73], 0, v[212:213]
	s_addc_u32 s3, s73, s3
	ds_read_b128 v[180:183], v144
	ds_read_b128 v[188:191], v145
	ds_read_b128 v[196:199], v159
	ds_read_b128 v[204:207], v160
	global_load_lds_dwordx4 v[214:215], off
	v_lshl_add_u64 v[212:213], s[2:3], 0, v[212:213]
	s_add_i32 m0, s42, 0xe000
	s_nop 0
	global_load_lds_dwordx4 v[212:213], off
	s_waitcnt lgkmcnt(4)
	s_waitcnt vmcnt(10)
	s_barrier
	s_waitcnt lgkmcnt(0)
	v_mfma_f32_16x16x32_bf16 v[128:131], v[164:167], v[180:183], v[128:131]
	ds_read_b128 v[184:187], v144 offset:1024
	v_mfma_f32_16x16x32_bf16 v[124:127], v[172:175], v[180:183], v[124:127]
	ds_read_b128 v[192:195], v145 offset:1024
	v_mfma_f32_16x16x32_bf16 v[120:123], v[164:167], v[188:191], v[120:123]
	ds_read_b128 v[200:203], v159 offset:1024
	v_mfma_f32_16x16x32_bf16 v[116:119], v[172:175], v[188:191], v[116:119]
	ds_read_b128 v[208:211], v160 offset:1024
	v_mfma_f32_16x16x32_bf16 v[104:107], v[164:167], v[196:199], v[104:107]
	v_mfma_f32_16x16x32_bf16 v[100:103], v[172:175], v[196:199], v[100:103]
	v_mfma_f32_16x16x32_bf16 v[88:91], v[164:167], v[204:207], v[88:91]
	v_mfma_f32_16x16x32_bf16 v[84:87], v[172:175], v[204:207], v[84:87]
	s_waitcnt lgkmcnt(0)
	v_mfma_f32_16x16x32_bf16 v[128:131], v[168:171], v[184:187], v[128:131]
	v_mfma_f32_16x16x32_bf16 v[124:127], v[176:179], v[184:187], v[124:127]
	v_mfma_f32_16x16x32_bf16 v[120:123], v[168:171], v[192:195], v[120:123]
	v_mfma_f32_16x16x32_bf16 v[116:119], v[176:179], v[192:195], v[116:119]
	v_mfma_f32_16x16x32_bf16 v[104:107], v[168:171], v[200:203], v[104:107]
	v_mfma_f32_16x16x32_bf16 v[100:103], v[176:179], v[200:203], v[100:103]
	v_mfma_f32_16x16x32_bf16 v[88:91], v[168:171], v[208:211], v[88:91]
	v_mfma_f32_16x16x32_bf16 v[84:87], v[176:179], v[208:211], v[84:87]
	s_barrier
	s_add_u32 s2, s70, s0
	s_mov_b32 m0, s43
	v_lshl_add_u64 v[228:229], s[70:71], 0, v[136:137]
	s_addc_u32 s3, s71, s1
	ds_read_b128 v[212:215], v161
	ds_read_b128 v[216:219], v161 offset:1024
	ds_read_b128 v[220:223], v161 offset:2048
	ds_read_b128 v[224:227], v161 offset:3072
	global_load_lds_dwordx4 v[228:229], off
	v_lshl_add_u64 v[230:231], s[2:3], 0, v[136:137]
	s_mov_b32 m0, s44
	s_nop 0
	global_load_lds_dwordx4 v[230:231], off
	s_waitcnt vmcnt(10)
	s_barrier
	s_waitcnt lgkmcnt(0)
	v_mfma_f32_16x16x32_bf16 v[112:115], v[212:215], v[180:183], v[112:115]
	v_mfma_f32_16x16x32_bf16 v[108:111], v[220:223], v[180:183], v[108:111]
	s_cmp_lt_u32 s68, s36
	s_cselect_b64 vcc, -1, 0
	v_mfma_f32_16x16x32_bf16 v[96:99], v[212:215], v[188:191], v[96:99]
	s_and_b64 s[70:71], vcc, exec
	s_cselect_b32 s70, s38, s37
	v_mfma_f32_16x16x32_bf16 v[92:95], v[220:223], v[188:191], v[92:95]
	s_sub_i32 s69, s68, s36
	s_min_u32 s94, s68, s69
	v_mfma_f32_16x16x32_bf16 v[80:83], v[212:215], v[196:199], v[80:83]
	s_and_b64 s[72:73], vcc, exec
	s_cselect_b32 s69, s64, s66
	v_mfma_f32_16x16x32_bf16 v[76:79], v[220:223], v[196:199], v[76:79]
	s_cselect_b32 s71, s52, s65
	s_lshl_b64 s[72:73], s[94:95], 7
	v_mfma_f32_16x16x32_bf16 v[72:75], v[212:215], v[204:207], v[72:75]
	v_cndmask_b32_e32 v2, v138, v0, vcc
	s_add_u32 s72, s71, s72
	v_mfma_f32_16x16x32_bf16 v[68:71], v[220:223], v[204:207], v[68:71]
	s_mov_b32 s71, s95
	v_mfma_f32_16x16x32_bf16 v[112:115], v[216:219], v[184:187], v[112:115]
	s_addc_u32 s73, s69, s73
	v_mfma_f32_16x16x32_bf16 v[108:111], v[224:227], v[184:187], v[108:111]
	v_lshlrev_b64 v[232:233], 1, v[2:3]
	v_mfma_f32_16x16x32_bf16 v[96:99], v[216:219], v[192:195], v[96:99]
	s_lshl_b64 s[70:71], s[70:71], 7
	v_mfma_f32_16x16x32_bf16 v[92:95], v[224:227], v[192:195], v[92:95]
	v_lshl_add_u64 v[234:235], s[72:73], 0, v[232:233]
	v_mfma_f32_16x16x32_bf16 v[80:83], v[216:219], v[200:203], v[80:83]
	s_add_u32 s72, s72, s70
	v_mfma_f32_16x16x32_bf16 v[76:79], v[224:227], v[200:203], v[76:79]
	s_mov_b32 m0, s42
	v_mfma_f32_16x16x32_bf16 v[72:75], v[216:219], v[208:211], v[72:75]
	s_addc_u32 s73, s73, s71
	v_mfma_f32_16x16x32_bf16 v[68:71], v[224:227], v[208:211], v[68:71]
	s_barrier
	ds_read_b128 v[180:183], v144 offset:16384
	ds_read_b128 v[188:191], v145 offset:16384
	ds_read_b128 v[196:199], v159 offset:16384
	ds_read_b128 v[204:207], v160 offset:16384
	global_load_lds_dwordx4 v[234:235], off
	v_lshl_add_u64 v[234:235], s[72:73], 0, v[232:233]
	s_mov_b32 m0, s39
	s_nop 0
	global_load_lds_dwordx4 v[234:235], off
	s_barrier
; #define LDA(dst, b, h) for (int m = 0; m < 4; ++m) for (int k = 0; k < 2; ++k) \
;     dst[m][k] = *reinterpret_cast<const bf16x8*>(SA(b, h) + lds_byte(wr * 64 + m * 16 + fr, k * 32 + fq * 8))
; #define LDB(dst, b, h) for (int n = 0; n < 2; ++n) for (int k = 0; k < 2; ++k) \
;     dst[n][k] = *reinterpret_cast<const bf16x8*>(SB(b, h) + lds_byte(wc * 32 + n * 16 + fr, k * 32 + fq * 8))
; #define MMA(ai, bj, At_, Bt_) do { __builtin_amdgcn_s_setprio(1); \
;     for (int m = 0; m < 4; ++m) for (int n = 0; n < 2; ++n) for (int k = 0; k < 2; ++k) \
;       acc[ai][bj][m][n] = __builtin_amdgcn_mfma_f32_16x16x32_bf16(Bt_[n][k], At_[m][k], acc[ai][bj][m][n], 0, 0, 0); \
;     __builtin_amdgcn_s_setprio(0); } while (0)
; #define WAIT_V(n) asm volatile("s_waitcnt vmcnt(" #n ")" ::: "memory")
; #define WAIT_L(n) asm volatile("s_waitcnt lgkmcnt(" #n ")" ::: "memory")
; #define BAR __builtin_amdgcn_s_barrier()
; #define SCHED __builtin_amdgcn_sched_barrier(0)
; #define STG(P, PTR, LD, O0) do { const bf16_t* _g = (PTR); \
;     __builtin_amdgcn_global_load_lds((const unsigned*)(_g + O0), (lds_u32*)((P) + swave * 1024), 16, 0, 0); \
;     __builtin_amdgcn_global_load_lds((const unsigned*)(_g + (size_t)64 * (LD) + O0), (lds_u32*)((P) + swave * 1024 + 8192), 16, 0, 0); } while (0)
; #define LDA(dst, b, h) for (int m = 0; m < 4; ++m) for (int k = 0; k < 2; ++k) \
;     dst[m][k] = *reinterpret_cast<const bf16x8*>(SA(b, h) + lds_byte(wr * 64 + m * 16 + fr, k * 32 + fq * 8))
; #define LDB(dst, b, h) for (int n = 0; n < 2; ++n) for (int k = 0; k < 2; ++k) \
;     dst[n][k] = *reinterpret_cast<const bf16x8*>(SB(b, h) + lds_byte(wc * 32 + n * 16 + fr, k * 32 + fq * 8))
; #define WAIT_V(n) asm volatile("s_waitcnt vmcnt(" #n ")" ::: "memory")
; #define WAIT_L(n) asm volatile("s_waitcnt lgkmcnt(" #n ")" ::: "memory")
; #define BAR __builtin_amdgcn_s_barrier()
; #define SCHED __builtin_amdgcn_sched_barrier(0)
; __device__ __forceinline__ void gemm_stream(int swave, const GemmJob& J, char* shm, int vb, int G) {
;     ...
;       BAR; WAIT_L(0); MMA(1, 0, At, B0); BAR; SCHED;
;       STG(SB(0, 1), b2 + hB, ldb, offB0);
;       WAIT_V(6); BAR; MMA(1, 1, At, B1); BAR;
;       LDB(B0, 1, 0); SCHED; LDA(At, 1, 0); STGA(SA(0, 1), xA, xA1, k2, 1);
;       WAIT_L(8); BAR; WAIT_L(0); MMA(0, 0, At, B0); BAR; SCHED;
;       LDB(B1, 1, 1); STG(SB(1, 0), b3, ldb, offB0);
	s_waitcnt lgkmcnt(0)
	v_mfma_f32_16x16x32_bf16 v[64:67], v[164:167], v[180:183], v[64:67]
	ds_read_b128 v[184:187], v144 offset:17408
	v_mfma_f32_16x16x32_bf16 v[60:63], v[172:175], v[180:183], v[60:63]
	ds_read_b128 v[192:195], v145 offset:17408
	v_mfma_f32_16x16x32_bf16 v[56:59], v[164:167], v[188:191], v[56:59]
	ds_read_b128 v[200:203], v159 offset:17408
	v_mfma_f32_16x16x32_bf16 v[52:55], v[172:175], v[188:191], v[52:55]
	ds_read_b128 v[208:211], v160 offset:17408
	v_mfma_f32_16x16x32_bf16 v[40:43], v[164:167], v[196:199], v[40:43]
	v_mfma_f32_16x16x32_bf16 v[36:39], v[172:175], v[196:199], v[36:39]
	v_mfma_f32_16x16x32_bf16 v[24:27], v[164:167], v[204:207], v[24:27]
	v_mfma_f32_16x16x32_bf16 v[20:23], v[172:175], v[204:207], v[20:23]
	s_waitcnt lgkmcnt(0)
	v_mfma_f32_16x16x32_bf16 v[64:67], v[168:171], v[184:187], v[64:67]
	v_mfma_f32_16x16x32_bf16 v[60:63], v[176:179], v[184:187], v[60:63]
	v_mfma_f32_16x16x32_bf16 v[56:59], v[168:171], v[192:195], v[56:59]
	v_mfma_f32_16x16x32_bf16 v[52:55], v[176:179], v[192:195], v[52:55]
	v_mfma_f32_16x16x32_bf16 v[40:43], v[168:171], v[200:203], v[40:43]
	v_mfma_f32_16x16x32_bf16 v[36:39], v[176:179], v[200:203], v[36:39]
	v_mfma_f32_16x16x32_bf16 v[24:27], v[168:171], v[208:211], v[24:27]
	v_mfma_f32_16x16x32_bf16 v[20:23], v[176:179], v[208:211], v[20:23]
	s_barrier
	s_add_u32 s2, s2, s0
	s_addc_u32 s3, s3, s1
	v_lshl_add_u64 v[234:235], s[2:3], 0, v[136:137]
	s_add_u32 s2, s2, s0
	s_mov_b32 m0, s45
	s_addc_u32 s3, s3, s1
	global_load_lds_dwordx4 v[234:235], off
	v_lshl_add_u64 v[236:237], s[2:3], 0, v[136:137]
	s_mov_b32 m0, s46
	s_nop 0
	global_load_lds_dwordx4 v[236:237], off
	s_waitcnt vmcnt(10)
	s_barrier
	v_mfma_f32_16x16x32_bf16 v[48:51], v[212:215], v[180:183], v[48:51]
	v_mfma_f32_16x16x32_bf16 v[44:47], v[220:223], v[180:183], v[44:47]
	v_mfma_f32_16x16x32_bf16 v[32:35], v[212:215], v[188:191], v[32:35]
	v_mfma_f32_16x16x32_bf16 v[28:31], v[220:223], v[188:191], v[28:31]
	v_mfma_f32_16x16x32_bf16 v[16:19], v[212:215], v[196:199], v[16:19]
	v_mfma_f32_16x16x32_bf16 v[12:15], v[220:223], v[196:199], v[12:15]
	v_mfma_f32_16x16x32_bf16 v[8:11], v[212:215], v[204:207], v[8:11]
	v_mfma_f32_16x16x32_bf16 v[4:7], v[220:223], v[204:207], v[4:7]
	v_mfma_f32_16x16x32_bf16 v[48:51], v[216:219], v[184:187], v[48:51]
	v_mfma_f32_16x16x32_bf16 v[44:47], v[224:227], v[184:187], v[44:47]
	v_mfma_f32_16x16x32_bf16 v[32:35], v[216:219], v[192:195], v[32:35]
	v_mfma_f32_16x16x32_bf16 v[28:31], v[224:227], v[192:195], v[28:31]
	v_mfma_f32_16x16x32_bf16 v[16:19], v[216:219], v[200:203], v[16:19]
	v_mfma_f32_16x16x32_bf16 v[12:15], v[224:227], v[200:203], v[12:15]
	v_mfma_f32_16x16x32_bf16 v[8:11], v[216:219], v[208:211], v[8:11]
	v_mfma_f32_16x16x32_bf16 v[4:7], v[224:227], v[208:211], v[4:7]
	s_barrier
	ds_read_b128 v[164:167], v162
	ds_read_b128 v[168:171], v162 offset:1024
	ds_read_b128 v[172:175], v162 offset:2048
	ds_read_b128 v[176:179], v162 offset:3072
	s_add_u32 s2, s72, s70
	s_addc_u32 s3, s73, s71
	v_lshl_add_u64 v[212:213], s[2:3], 0, v[232:233]
	s_add_u32 s2, s2, s70
	s_mov_b32 m0, s47
	s_addc_u32 s3, s3, s71
	ds_read_b128 v[180:183], v144 offset:32768
	ds_read_b128 v[188:191], v145 offset:32768
	ds_read_b128 v[196:199], v159 offset:32768
	ds_read_b128 v[204:207], v160 offset:32768
	global_load_lds_dwordx4 v[212:213], off
	v_lshl_add_u64 v[212:213], s[2:3], 0, v[232:233]
	s_mov_b32 m0, s48
	s_nop 0
	global_load_lds_dwordx4 v[212:213], off
	s_waitcnt lgkmcnt(4)
	s_waitcnt vmcnt(10)
	s_barrier
	s_waitcnt lgkmcnt(0)
	v_mfma_f32_16x16x32_bf16 v[128:131], v[164:167], v[180:183], v[128:131]
	ds_read_b128 v[184:187], v144 offset:33792
	v_mfma_f32_16x16x32_bf16 v[124:127], v[172:175], v[180:183], v[124:127]
	ds_read_b128 v[192:195], v145 offset:33792
	v_mfma_f32_16x16x32_bf16 v[120:123], v[164:167], v[188:191], v[120:123]
	ds_read_b128 v[200:203], v159 offset:33792
	v_mfma_f32_16x16x32_bf16 v[116:119], v[172:175], v[188:191], v[116:119]
	ds_read_b128 v[208:211], v160 offset:33792
	v_mfma_f32_16x16x32_bf16 v[104:107], v[164:167], v[196:199], v[104:107]
	v_mfma_f32_16x16x32_bf16 v[100:103], v[172:175], v[196:199], v[100:103]
	v_mfma_f32_16x16x32_bf16 v[88:91], v[164:167], v[204:207], v[88:91]
	v_mfma_f32_16x16x32_bf16 v[84:87], v[172:175], v[204:207], v[84:87]
	s_waitcnt lgkmcnt(0)
	v_mfma_f32_16x16x32_bf16 v[128:131], v[168:171], v[184:187], v[128:131]
	v_mfma_f32_16x16x32_bf16 v[124:127], v[176:179], v[184:187], v[124:127]
	v_mfma_f32_16x16x32_bf16 v[120:123], v[168:171], v[192:195], v[120:123]
	v_mfma_f32_16x16x32_bf16 v[116:119], v[176:179], v[192:195], v[116:119]
	v_mfma_f32_16x16x32_bf16 v[104:107], v[168:171], v[200:203], v[104:107]
	v_mfma_f32_16x16x32_bf16 v[100:103], v[176:179], v[200:203], v[100:103]
	v_mfma_f32_16x16x32_bf16 v[88:91], v[168:171], v[208:211], v[88:91]
	v_mfma_f32_16x16x32_bf16 v[84:87], v[176:179], v[208:211], v[84:87]
	s_barrier
	v_lshl_add_u64 v[228:229], v[228:229], 0, s[22:23]
	s_add_i32 m0, s42, 0x18000
	ds_read_b128 v[212:215], v163
	ds_read_b128 v[216:219], v163 offset:1024
	ds_read_b128 v[220:223], v163 offset:2048
	ds_read_b128 v[224:227], v163 offset:3072
	global_load_lds_dwordx4 v[228:229], off
	v_lshl_add_u64 v[228:229], v[230:231], 0, s[22:23]
	s_add_i32 m0, s42, 0x1a000
	s_nop 0
	global_load_lds_dwordx4 v[228:229], off
	s_waitcnt vmcnt(10)
	s_barrier
; #define LDA(dst, b, h) for (int m = 0; m < 4; ++m) for (int k = 0; k < 2; ++k) \
;     dst[m][k] = *reinterpret_cast<const bf16x8*>(SA(b, h) + lds_byte(wr * 64 + m * 16 + fr, k * 32 + fq * 8))
; #define MMA(ai, bj, At_, Bt_) do { __builtin_amdgcn_s_setprio(1); \
;     for (int m = 0; m < 4; ++m) for (int n = 0; n < 2; ++n) for (int k = 0; k < 2; ++k) \
;       acc[ai][bj][m][n] = __builtin_amdgcn_mfma_f32_16x16x32_bf16(Bt_[n][k], At_[m][k], acc[ai][bj][m][n], 0, 0, 0); \
;     __builtin_amdgcn_s_setprio(0); } while (0)
; #define WAIT_V(n) asm volatile("s_waitcnt vmcnt(" #n ")" ::: "memory")
; #define WAIT_L(n) asm volatile("s_waitcnt lgkmcnt(" #n ")" ::: "memory")
; #define BAR __builtin_amdgcn_s_barrier()
; #define SCHED __builtin_amdgcn_sched_barrier(0)
; #define STG(P, PTR, LD, O0) do { const bf16_t* _g = (PTR); \
;     __builtin_amdgcn_global_load_lds((const unsigned*)(_g + O0), (lds_u32*)((P) + swave * 1024), 16, 0, 0); \
;     __builtin_amdgcn_global_load_lds((const unsigned*)(_g + (size_t)64 * (LD) + O0), (lds_u32*)((P) + swave * 1024 + 8192), 16, 0, 0); } while (0)
; #define LDA(dst, b, h) for (int m = 0; m < 4; ++m) for (int k = 0; k < 2; ++k) \
;     dst[m][k] = *reinterpret_cast<const bf16x8*>(SA(b, h) + lds_byte(wr * 64 + m * 16 + fr, k * 32 + fq * 8))
; #define MMA(ai, bj, At_, Bt_) do { __builtin_amdgcn_s_setprio(1); \
;     for (int m = 0; m < 4; ++m) for (int n = 0; n < 2; ++n) for (int k = 0; k < 2; ++k) \
;       acc[ai][bj][m][n] = __builtin_amdgcn_mfma_f32_16x16x32_bf16(Bt_[n][k], At_[m][k], acc[ai][bj][m][n], 0, 0, 0); \
;     __builtin_amdgcn_s_setprio(0); } while (0)
; #define WAIT_V(n) asm volatile("s_waitcnt vmcnt(" #n ")" ::: "memory")
; #define WAIT_L(n) asm volatile("s_waitcnt lgkmcnt(" #n ")" ::: "memory")
; #define BAR __builtin_amdgcn_s_barrier()
; #define SCHED __builtin_amdgcn_sched_barrier(0)
; __device__ __forceinline__ void gemm_stream(int swave, const GemmJob& J, char* shm, int vb, int G) {
;     ...
;       BAR; WAIT_L(0); MMA(0, 1, At, B1); BAR;
;       LDA(At, 1, 1); STGA(SA(1, 0), xA, xA1, k2 + 1, 0);
;       BAR; WAIT_L(0); MMA(1, 0, At, B0); BAR; SCHED;
;       STG(SB(1, 1), b3 + hB, ldb, offB0);
;       WAIT_V(6); BAR; MMA(1, 1, At, B1); BAR;
	s_waitcnt lgkmcnt(0)
	v_mfma_f32_16x16x32_bf16 v[112:115], v[212:215], v[180:183], v[112:115]
	v_mfma_f32_16x16x32_bf16 v[108:111], v[220:223], v[180:183], v[108:111]
	s_or_b32 s68, s68, 1
	s_cmp_lt_u32 s68, s36
	v_mfma_f32_16x16x32_bf16 v[96:99], v[212:215], v[188:191], v[96:99]
	s_cselect_b64 vcc, -1, 0
	s_and_b64 s[2:3], vcc, exec
	v_mfma_f32_16x16x32_bf16 v[92:95], v[220:223], v[188:191], v[92:95]
	s_cselect_b32 s69, s38, s37
	s_sub_i32 s2, s68, s36
	v_mfma_f32_16x16x32_bf16 v[80:83], v[212:215], v[196:199], v[80:83]
	s_min_u32 s94, s68, s2
	s_and_b64 s[2:3], vcc, exec
	v_mfma_f32_16x16x32_bf16 v[76:79], v[220:223], v[196:199], v[76:79]
	s_cselect_b32 s64, s64, s66
	s_cselect_b32 s52, s52, s65
	v_mfma_f32_16x16x32_bf16 v[72:75], v[212:215], v[204:207], v[72:75]
	s_lshl_b64 s[2:3], s[94:95], 7
	v_cndmask_b32_e32 v2, v138, v0, vcc
	v_mfma_f32_16x16x32_bf16 v[68:71], v[220:223], v[204:207], v[68:71]
	s_add_u32 s2, s52, s2
	v_mfma_f32_16x16x32_bf16 v[112:115], v[216:219], v[184:187], v[112:115]
	s_addc_u32 s3, s64, s3
	v_mfma_f32_16x16x32_bf16 v[108:111], v[224:227], v[184:187], v[108:111]
	v_lshlrev_b64 v[228:229], 1, v[2:3]
	v_mfma_f32_16x16x32_bf16 v[96:99], v[216:219], v[192:195], v[96:99]
	s_lshl_b32 s52, s69, 7
	v_mfma_f32_16x16x32_bf16 v[92:95], v[224:227], v[192:195], v[92:95]
	v_lshl_add_u64 v[230:231], s[2:3], 0, v[228:229]
	v_mfma_f32_16x16x32_bf16 v[80:83], v[216:219], v[200:203], v[80:83]
	s_add_u32 s2, s2, s52
	v_mfma_f32_16x16x32_bf16 v[76:79], v[224:227], v[200:203], v[76:79]
	s_mov_b32 m0, s54
	v_mfma_f32_16x16x32_bf16 v[72:75], v[216:219], v[208:211], v[72:75]
	s_addc_u32 s3, s3, 0
	v_mfma_f32_16x16x32_bf16 v[68:71], v[224:227], v[208:211], v[68:71]
	s_barrier
	ds_read_b128 v[180:183], v144 offset:49152
	ds_read_b128 v[188:191], v145 offset:49152
	ds_read_b128 v[196:199], v159 offset:49152
	ds_read_b128 v[204:207], v160 offset:49152
	global_load_lds_dwordx4 v[230:231], off
	v_lshl_add_u64 v[228:229], s[2:3], 0, v[228:229]
	s_mov_b32 m0, s55
	s_nop 0
	global_load_lds_dwordx4 v[228:229], off
	s_barrier
	s_waitcnt lgkmcnt(0)
	v_mfma_f32_16x16x32_bf16 v[64:67], v[164:167], v[180:183], v[64:67]
	ds_read_b128 v[184:187], v144 offset:50176
	v_mfma_f32_16x16x32_bf16 v[60:63], v[172:175], v[180:183], v[60:63]
	ds_read_b128 v[192:195], v145 offset:50176
	v_mfma_f32_16x16x32_bf16 v[56:59], v[164:167], v[188:191], v[56:59]
	ds_read_b128 v[200:203], v159 offset:50176
	v_mfma_f32_16x16x32_bf16 v[52:55], v[172:175], v[188:191], v[52:55]
	ds_read_b128 v[208:211], v160 offset:50176
	v_mfma_f32_16x16x32_bf16 v[40:43], v[164:167], v[196:199], v[40:43]
	v_mfma_f32_16x16x32_bf16 v[36:39], v[172:175], v[196:199], v[36:39]
	v_mfma_f32_16x16x32_bf16 v[24:27], v[164:167], v[204:207], v[24:27]
	v_mfma_f32_16x16x32_bf16 v[20:23], v[172:175], v[204:207], v[20:23]
	s_waitcnt lgkmcnt(0)
	v_mfma_f32_16x16x32_bf16 v[64:67], v[168:171], v[184:187], v[64:67]
	v_mfma_f32_16x16x32_bf16 v[60:63], v[176:179], v[184:187], v[60:63]
	v_mfma_f32_16x16x32_bf16 v[56:59], v[168:171], v[192:195], v[56:59]
	v_mfma_f32_16x16x32_bf16 v[52:55], v[176:179], v[192:195], v[52:55]
	v_mfma_f32_16x16x32_bf16 v[40:43], v[168:171], v[200:203], v[40:43]
	v_mfma_f32_16x16x32_bf16 v[36:39], v[176:179], v[200:203], v[36:39]
	v_mfma_f32_16x16x32_bf16 v[24:27], v[168:171], v[208:211], v[24:27]
	v_mfma_f32_16x16x32_bf16 v[20:23], v[176:179], v[208:211], v[20:23]
	s_barrier
	v_lshl_add_u64 v[164:165], v[234:235], 0, s[22:23]
	s_add_i32 m0, s42, 0x1c000
	s_nop 0
	global_load_lds_dwordx4 v[164:165], off
	v_lshl_add_u64 v[164:165], v[236:237], 0, s[22:23]
	s_add_i32 m0, s42, 0x1e000
	s_nop 0
	global_load_lds_dwordx4 v[164:165], off
	s_waitcnt vmcnt(10)
	s_barrier
	v_mfma_f32_16x16x32_bf16 v[48:51], v[212:215], v[180:183], v[48:51]
	v_mfma_f32_16x16x32_bf16 v[44:47], v[220:223], v[180:183], v[44:47]
	s_add_i32 s29, s29, 2
	v_mfma_f32_16x16x32_bf16 v[32:35], v[212:215], v[188:191], v[32:35]
	s_add_u32 s20, s20, 0x100
	v_mfma_f32_16x16x32_bf16 v[28:31], v[220:223], v[188:191], v[28:31]
	s_addc_u32 s21, s21, 0
	v_mfma_f32_16x16x32_bf16 v[16:19], v[212:215], v[196:199], v[16:19]
	s_cmp_ge_u32 s33, s49
	v_mfma_f32_16x16x32_bf16 v[12:15], v[220:223], v[196:199], v[12:15]
	s_mov_b32 s2, s33
	v_mfma_f32_16x16x32_bf16 v[8:11], v[212:215], v[204:207], v[8:11]
	v_mfma_f32_16x16x32_bf16 v[4:7], v[220:223], v[204:207], v[4:7]
	v_mfma_f32_16x16x32_bf16 v[48:51], v[216:219], v[184:187], v[48:51]
	v_mfma_f32_16x16x32_bf16 v[44:47], v[224:227], v[184:187], v[44:47]
	v_mfma_f32_16x16x32_bf16 v[32:35], v[216:219], v[192:195], v[32:35]
	v_mfma_f32_16x16x32_bf16 v[28:31], v[224:227], v[192:195], v[28:31]
	v_mfma_f32_16x16x32_bf16 v[16:19], v[216:219], v[200:203], v[16:19]
	v_mfma_f32_16x16x32_bf16 v[12:15], v[224:227], v[200:203], v[12:15]
	v_mfma_f32_16x16x32_bf16 v[8:11], v[216:219], v[208:211], v[8:11]
	v_mfma_f32_16x16x32_bf16 v[4:7], v[224:227], v[208:211], v[4:7]
	s_barrier
; __device__ __forceinline__ unsigned pk2(float lo, float hi) { f32x2_t v = {lo, hi}; bf16x2_t b = __builtin_convertvector(v, bf16x2_t); return __builtin_bit_cast(unsigned, b); }
; #define WAIT_V(n) asm volatile("s_waitcnt vmcnt(" #n ")" ::: "memory")
; #define BAR __builtin_amdgcn_s_barrier()
; #define WAIT_V(n) asm volatile("s_waitcnt vmcnt(" #n ")" ::: "memory")
; #define BAR __builtin_amdgcn_s_barrier()
; __device__ __forceinline__ void gemm_stream(int swave, const GemmJob& J, char* shm, int vb, int G) {
;     ...
;     {
;       bf16_t* C = (bf16_t*)((char*)J.c0 + (size_t)cg * J.strideC);
; #pragma unroll
;       for (int ai = 0; ai < 2; ++ai)
; #pragma unroll
;         for (int m = 0; m < 4; ++m)
; #pragma unroll
;           for (int bj = 0; bj < 2; ++bj) {
;             const f32x4 v0 = acc[ai][bj][m][0], v1 = acc[ai][bj][m][1];
;             uint4 o; o.x = pk2(v0[0], v0[1]); o.y = pk2(v0[2], v0[3]); o.z = pk2(v1[0], v1[1]); o.w = pk2(v1[2], v1[3]);
;             *(uint4*)(C + (size_t)(cbrow + ai * 128 + wr * 64 + m * 16 + fr) * J.ldc + cbcol + bj * 128 + wc * 32 + fq * 8) = o;
;           }
;     }
;     if (!has_next) break;
; #pragma unroll
;     for (int a_ = 0; a_ < 2; ++a_)
; #pragma unroll
;       for (int b_ = 0; b_ < 2; ++b_)
; #pragma unroll
;         for (int m = 0; m < 4; ++m)
; #pragma unroll
;           for (int n = 0; n < 2; ++n) acc[a_][b_][m][n] = (f32x4){0.f, 0.f, 0.f, 0.f};
;     id = nid; cg = ng; cbrow = nbrow; cbcol = nbcol; cA = nA; cA1 = nA1; cB = nB;
;   }
;   WAIT_V(0);
;   if (wr == 0) BAR;
	s_cbranch_scc0 .LBB0_729
	v_add_u32_e32 v164, s5, v1
	s_ashr_i32 s5, s4, 31
	s_lshl_b64 s[2:3], s[4:5], 1
	v_ashrrev_i32_e32 v2, 31, v164
	s_add_u32 s2, s50, s2
	v_cvt_pk_bf16_f32 v128, v128, v129
	v_cvt_pk_bf16_f32 v129, v130, v131
	v_cvt_pk_bf16_f32 v130, v124, v125
	v_mul_lo_u32 v2, v2, s18
	v_mad_u64_u32 v[124:125], s[4:5], v164, s18, 0
	s_addc_u32 s3, s51, s3
	v_add_u32_e32 v125, v125, v2
	v_lshl_add_u64 v[124:125], v[124:125], 1, s[2:3]
	v_mov_b32_e32 v141, v3
	v_lshl_add_u64 v[124:125], v[124:125], 0, v[140:141]
	v_mov_b32_e32 v143, v3
	v_lshl_add_u64 v[124:125], v[124:125], 0, v[142:143]
	s_lshl_b32 s2, s18, 5
	s_mov_b32 s3, 0
	s_mul_i32 s4, s18, 0xa0
	s_mov_b32 s5, 0
	v_cvt_pk_bf16_f32 v112, v112, v113
	v_cvt_pk_bf16_f32 v113, v114, v115
	v_cvt_pk_bf16_f32 v114, v108, v109
	v_cvt_pk_bf16_f32 v115, v110, v111
	global_store_dwordx4 v[124:125], v[112:115], off offset:256
	v_cvt_pk_bf16_f32 v131, v126, v127
	v_cvt_pk_bf16_f32 v96, v96, v97
	v_lshl_add_u64 v[112:113], v[124:125], 0, s[2:3]
	v_cvt_pk_bf16_f32 v97, v98, v99
	v_cvt_pk_bf16_f32 v98, v92, v93
	v_cvt_pk_bf16_f32 v99, v94, v95
	global_store_dwordx4 v[124:125], v[128:131], off
	global_store_dwordx4 v[112:113], v[96:99], off offset:256
	v_cvt_pk_bf16_f32 v108, v120, v121
	v_cvt_pk_bf16_f32 v109, v122, v123
	v_lshl_add_u64 v[96:97], v[112:113], 0, s[2:3]
	v_cvt_pk_bf16_f32 v110, v116, v117
	v_cvt_pk_bf16_f32 v111, v118, v119
	v_cvt_pk_bf16_f32 v80, v80, v81
	v_cvt_pk_bf16_f32 v81, v82, v83
	v_cvt_pk_bf16_f32 v82, v76, v77
	v_cvt_pk_bf16_f32 v83, v78, v79
	global_store_dwordx4 v[112:113], v[108:111], off
	global_store_dwordx4 v[96:97], v[80:83], off offset:256
	v_cvt_pk_bf16_f32 v64, v64, v65
	v_cvt_pk_bf16_f32 v65, v66, v67
	v_lshl_add_u64 v[80:81], v[96:97], 0, s[2:3]
	v_cvt_pk_bf16_f32 v66, v60, v61
	v_lshl_add_u64 v[60:61], v[80:81], 0, s[4:5]
	v_cvt_pk_bf16_f32 v72, v72, v73
	v_cvt_pk_bf16_f32 v73, v74, v75
	v_cvt_pk_bf16_f32 v74, v68, v69
	v_cvt_pk_bf16_f32 v67, v62, v63
	v_cvt_pk_bf16_f32 v92, v104, v105
	v_cvt_pk_bf16_f32 v93, v106, v107
	v_cvt_pk_bf16_f32 v94, v100, v101
	v_cvt_pk_bf16_f32 v95, v102, v103
	v_cvt_pk_bf16_f32 v76, v88, v89
	v_cvt_pk_bf16_f32 v77, v90, v91
	v_cvt_pk_bf16_f32 v78, v84, v85
	v_cvt_pk_bf16_f32 v79, v86, v87
	v_cvt_pk_bf16_f32 v75, v70, v71
	v_cvt_pk_bf16_f32 v48, v48, v49
	v_cvt_pk_bf16_f32 v49, v50, v51
	v_cvt_pk_bf16_f32 v50, v44, v45
	v_cvt_pk_bf16_f32 v51, v46, v47
	global_store_dwordx4 v[96:97], v[92:95], off
	global_store_dwordx4 v[80:81], v[76:79], off
	global_store_dwordx4 v[80:81], v[72:75], off offset:256
	global_store_dwordx4 v[60:61], v[48:51], off offset:256
	v_cvt_pk_bf16_f32 v32, v32, v33
	v_cvt_pk_bf16_f32 v33, v34, v35
	v_lshl_add_u64 v[48:49], v[60:61], 0, s[2:3]
	v_cvt_pk_bf16_f32 v34, v28, v29
	v_cvt_pk_bf16_f32 v35, v30, v31
	global_store_dwordx4 v[60:61], v[64:67], off
	global_store_dwordx4 v[48:49], v[32:35], off offset:256
	v_cvt_pk_bf16_f32 v44, v56, v57
	v_cvt_pk_bf16_f32 v45, v58, v59
	v_lshl_add_u64 v[32:33], v[48:49], 0, s[2:3]
	v_cvt_pk_bf16_f32 v46, v52, v53
	v_cvt_pk_bf16_f32 v47, v54, v55
	v_cvt_pk_bf16_f32 v16, v16, v17
	v_cvt_pk_bf16_f32 v17, v18, v19
	v_cvt_pk_bf16_f32 v18, v12, v13
	v_cvt_pk_bf16_f32 v19, v14, v15
	global_store_dwordx4 v[48:49], v[44:47], off
	global_store_dwordx4 v[32:33], v[16:19], off offset:256
	v_cvt_pk_bf16_f32 v28, v40, v41
	v_cvt_pk_bf16_f32 v29, v42, v43
	v_lshl_add_u64 v[16:17], v[32:33], 0, s[2:3]
	v_cvt_pk_bf16_f32 v30, v36, v37
	v_cvt_pk_bf16_f32 v31, v38, v39
	v_cvt_pk_bf16_f32 v12, v24, v25
	v_cvt_pk_bf16_f32 v13, v26, v27
	v_cvt_pk_bf16_f32 v14, v20, v21
	v_cvt_pk_bf16_f32 v15, v22, v23
	v_cvt_pk_bf16_f32 v8, v8, v9
	v_cvt_pk_bf16_f32 v9, v10, v11
	v_cvt_pk_bf16_f32 v10, v4, v5
	v_cvt_pk_bf16_f32 v11, v6, v7
	s_and_b64 vcc, exec, s[6:7]
	s_mov_b64 s[2:3], s[14:15]
	s_mov_b64 s[16:17], s[12:13]
	s_mov_b64 s[8:9], s[10:11]
	s_mov_b32 s4, s56
	s_mov_b32 s5, s28
	global_store_dwordx4 v[32:33], v[28:31], off
	global_store_dwordx4 v[16:17], v[12:15], off
	global_store_dwordx4 v[16:17], v[8:11], off offset:256
	s_cbranch_vccz .LBB0_726
	s_waitcnt vmcnt(0)
	s_movk_i32 s66, 0x100
	v_cmp_gt_u32_e32 vcc, s66, v135
	s_and_saveexec_b64 s[0:1], vcc
	s_cbranch_execz .LBB0_733
	s_barrier
